# in-proj epilogue: row*ldc store addressing with one 24-bit multiply instead of the 64x64-bit multiply emulation (v_mul_lo_u32 x2-3 + v_mad_u64_u32 + v_add3), 16 sites per unit
# speedup vs baseline: 1.0098x; 1.0014x over previous
; __device__ __forceinline__ unsigned cvt_pk_bf16(float lo, float hi) { unsigned r; asm volatile("v_cvt_pk_bf16_f32 %0, %1, %2" : "=v"(r) : "v"(lo), "v"(hi)); return r; }
; __device__ __forceinline__ float sigmoid_f(float x) { return __builtin_amdgcn_rcpf(1.0f + __builtin_amdgcn_exp2f(-1.4426950408889634f * x)); }
;     __device__ __forceinline__ void operator()(const f32x4 (&acc)[2][2][4][2], const Unit& u, int wr, int wc, int fr, int fq) const {
;     ...
;         const int row0 = u.pm * BM + wr * 64 + fr, c0 = wc * 32 + 8 * fq;
; #pragma unroll
;         for (int bj = 0; bj < 2; ++bj) {
;             const int c = c0 + bj * HALF;
;             if (mode == 2 && c >= 64) continue;
;             f32x4 b0 = (f32x4){0.f, 0.f, 0.f, 0.f}, b1 = b0;
;             if (mode == 1) { b0 = *(const f32x4*)(bgate + ct + c); b1 = *(const f32x4*)(bgate + ct + c + 4); }
; #pragma unroll
;             for (int ai = 0; ai < 2; ++ai)
; #pragma unroll
;                 for (int m = 0; m < 4; ++m) {
;                     f32x4 v0 = acc[ai][bj][m][0] + b0, v1 = acc[ai][bj][m][1] + b1;
;                     if (mode == 1) {
; #pragma unroll
;                         for (int e = 0; e < 4; ++e) { v0[e] = sigmoid_f(v0[e]); v1[e] = sigmoid_f(v1[e]); }
;                     }
;                     u32x4 w; w.x = cvt_pk_bf16(v0[0], v0[1]); w.y = cvt_pk_bf16(v0[2], v0[3]); w.z = cvt_pk_bf16(v1[0], v1[1]); w.w = cvt_pk_bf16(v1[2], v1[3]);
;                     *(u32x4*)(dst + (size_t)(row0 + ai * HALF + m * 16) * ldc + ct + c) = w;
;                 }
.LBB0_108:
	v_cvt_pk_bf16_f32 v124, v124, v125
	v_cvt_pk_bf16_f32 v125, v126, v127
	v_cvt_pk_bf16_f32 v126, v158, v159
	v_cvt_pk_bf16_f32 v127, v122, v123
	v_ashrrev_i32_e32 v122, 31, v165
	v_lshlrev_b32_e32 v144, 1, v146
	v_mul_u32_u24_e32 v158, s82, v165
	v_mov_b32_e32 v159, 0
	v_lshl_add_u64 v[120:121], s[86:87], 0, v[144:145]
	v_lshl_add_u64 v[158:159], v[158:159], 1, v[120:121]
	v_pk_add_f32 v[118:119], v[118:119], v[134:135]
	v_pk_add_f32 v[116:117], v[116:117], v[132:133]
	v_pk_add_f32 v[114:115], v[114:115], v[130:131]
	s_and_b64 vcc, exec, s[4:5]
	v_pk_add_f32 v[112:113], v[112:113], v[128:129]
	global_store_dwordx4 v[158:159], v[124:127], off
	s_cbranch_vccnz .LBB0_110
	v_mul_f32_e32 v116, 0xbfb8aa3b, v116
	v_mul_f32_e32 v112, 0xbfb8aa3b, v112
	v_mul_f32_e32 v117, 0xbfb8aa3b, v117
	v_mul_f32_e32 v113, 0xbfb8aa3b, v113
	v_mul_f32_e32 v118, 0xbfb8aa3b, v118
	v_mul_f32_e32 v114, 0xbfb8aa3b, v114
	v_mul_f32_e32 v119, 0xbfb8aa3b, v119
	v_mul_f32_e32 v115, 0xbfb8aa3b, v115
	v_exp_f32_e32 v116, v116
	v_exp_f32_e32 v112, v112
	v_exp_f32_e32 v117, v117
	v_exp_f32_e32 v113, v113
	v_exp_f32_e32 v118, v118
	v_exp_f32_e32 v114, v114
	v_exp_f32_e32 v119, v119
	v_exp_f32_e32 v115, v115
	v_add_f32_e32 v116, 1.0, v116
	v_add_f32_e32 v112, 1.0, v112
	v_add_f32_e32 v117, 1.0, v117
	v_add_f32_e32 v113, 1.0, v113
	v_add_f32_e32 v118, 1.0, v118
	v_add_f32_e32 v114, 1.0, v114
	v_add_f32_e32 v119, 1.0, v119
	v_add_f32_e32 v115, 1.0, v115
	v_rcp_f32_e32 v116, v116
	v_rcp_f32_e32 v112, v112
	v_rcp_f32_e32 v117, v117
	v_rcp_f32_e32 v113, v113
	v_rcp_f32_e32 v118, v118
	v_rcp_f32_e32 v114, v114
	v_rcp_f32_e32 v119, v119
	v_rcp_f32_e32 v115, v115
.LBB0_110:
	v_cvt_pk_bf16_f32 v116, v116, v117
	v_cvt_pk_bf16_f32 v117, v118, v119
	v_cvt_pk_bf16_f32 v118, v112, v113
	v_or_b32_e32 v112, 16, v165
	v_cvt_pk_bf16_f32 v119, v114, v115
	v_mul_u32_u24_e32 v112, s82, v112
	v_mov_b32_e32 v113, 0
	v_lshl_add_u64 v[112:113], v[112:113], 1, v[120:121]
	v_pk_add_f32 v[110:111], v[110:111], v[134:135]
	v_pk_add_f32 v[108:109], v[108:109], v[132:133]
	v_pk_add_f32 v[106:107], v[106:107], v[130:131]
	s_and_b64 vcc, exec, s[4:5]
	v_pk_add_f32 v[104:105], v[104:105], v[128:129]
	global_store_dwordx4 v[112:113], v[116:119], off
	s_cbranch_vccnz .LBB0_112
	v_mul_f32_e32 v108, 0xbfb8aa3b, v108
	v_mul_f32_e32 v104, 0xbfb8aa3b, v104
	v_mul_f32_e32 v109, 0xbfb8aa3b, v109
	v_mul_f32_e32 v105, 0xbfb8aa3b, v105
	v_mul_f32_e32 v110, 0xbfb8aa3b, v110
	v_mul_f32_e32 v106, 0xbfb8aa3b, v106
	v_mul_f32_e32 v111, 0xbfb8aa3b, v111
	v_mul_f32_e32 v107, 0xbfb8aa3b, v107
	v_exp_f32_e32 v108, v108
	v_exp_f32_e32 v104, v104
	v_exp_f32_e32 v109, v109
	v_exp_f32_e32 v105, v105
	v_exp_f32_e32 v110, v110
	v_exp_f32_e32 v106, v106
	v_exp_f32_e32 v111, v111
	v_exp_f32_e32 v107, v107
	v_add_f32_e32 v108, 1.0, v108
	v_add_f32_e32 v104, 1.0, v104
	v_add_f32_e32 v109, 1.0, v109
	v_add_f32_e32 v105, 1.0, v105
	v_add_f32_e32 v110, 1.0, v110
	v_add_f32_e32 v106, 1.0, v106
	v_add_f32_e32 v111, 1.0, v111
	v_add_f32_e32 v107, 1.0, v107
	v_rcp_f32_e32 v108, v108
	v_rcp_f32_e32 v104, v104
	v_rcp_f32_e32 v109, v109
	v_rcp_f32_e32 v105, v105
	v_rcp_f32_e32 v110, v110
	v_rcp_f32_e32 v106, v106
	v_rcp_f32_e32 v111, v111
	v_rcp_f32_e32 v107, v107
.LBB0_112:
	v_cvt_pk_bf16_f32 v108, v108, v109
	v_cvt_pk_bf16_f32 v109, v110, v111
	v_cvt_pk_bf16_f32 v110, v104, v105
	v_or_b32_e32 v104, 32, v165
	v_cvt_pk_bf16_f32 v111, v106, v107
	v_mul_u32_u24_e32 v104, s82, v104
	v_mov_b32_e32 v105, 0
	v_lshl_add_u64 v[104:105], v[104:105], 1, v[120:121]
	v_pk_add_f32 v[102:103], v[102:103], v[134:135]
	v_pk_add_f32 v[100:101], v[100:101], v[132:133]
	v_pk_add_f32 v[98:99], v[98:99], v[130:131]
	s_and_b64 vcc, exec, s[4:5]
	v_pk_add_f32 v[96:97], v[96:97], v[128:129]
	global_store_dwordx4 v[104:105], v[108:111], off
	s_cbranch_vccnz .LBB0_114
	v_mul_f32_e32 v100, 0xbfb8aa3b, v100
	v_mul_f32_e32 v96, 0xbfb8aa3b, v96
	v_mul_f32_e32 v101, 0xbfb8aa3b, v101
	v_mul_f32_e32 v97, 0xbfb8aa3b, v97
	v_mul_f32_e32 v102, 0xbfb8aa3b, v102
	v_mul_f32_e32 v98, 0xbfb8aa3b, v98
	v_mul_f32_e32 v103, 0xbfb8aa3b, v103
	v_mul_f32_e32 v99, 0xbfb8aa3b, v99
	v_exp_f32_e32 v100, v100
	v_exp_f32_e32 v96, v96
	v_exp_f32_e32 v101, v101
	v_exp_f32_e32 v97, v97
	v_exp_f32_e32 v102, v102
	v_exp_f32_e32 v98, v98
	v_exp_f32_e32 v103, v103
	v_exp_f32_e32 v99, v99
	v_add_f32_e32 v100, 1.0, v100
	v_add_f32_e32 v96, 1.0, v96
	v_add_f32_e32 v101, 1.0, v101
	v_add_f32_e32 v97, 1.0, v97
	v_add_f32_e32 v102, 1.0, v102
	v_add_f32_e32 v98, 1.0, v98
	v_add_f32_e32 v103, 1.0, v103
	v_add_f32_e32 v99, 1.0, v99
	v_rcp_f32_e32 v100, v100
	v_rcp_f32_e32 v96, v96
	v_rcp_f32_e32 v101, v101
	v_rcp_f32_e32 v97, v97
	v_rcp_f32_e32 v102, v102
	v_rcp_f32_e32 v98, v98
	v_rcp_f32_e32 v103, v103
	v_rcp_f32_e32 v99, v99
.LBB0_114:
	v_cvt_pk_bf16_f32 v100, v100, v101
	v_cvt_pk_bf16_f32 v101, v102, v103
	v_cvt_pk_bf16_f32 v102, v96, v97
	v_or_b32_e32 v96, 48, v165
	v_cvt_pk_bf16_f32 v103, v98, v99
	v_mul_u32_u24_e32 v96, s82, v96
	v_mov_b32_e32 v97, 0
	v_lshl_add_u64 v[96:97], v[96:97], 1, v[120:121]
	v_pk_add_f32 v[94:95], v[94:95], v[134:135]
	v_pk_add_f32 v[92:93], v[92:93], v[132:133]
	v_pk_add_f32 v[90:91], v[90:91], v[130:131]
	s_and_b64 vcc, exec, s[4:5]
	v_pk_add_f32 v[88:89], v[88:89], v[128:129]
	global_store_dwordx4 v[96:97], v[100:103], off
	s_cbranch_vccnz .LBB0_116
	v_mul_f32_e32 v92, 0xbfb8aa3b, v92
	v_mul_f32_e32 v88, 0xbfb8aa3b, v88
	v_mul_f32_e32 v93, 0xbfb8aa3b, v93
	v_mul_f32_e32 v89, 0xbfb8aa3b, v89
	v_mul_f32_e32 v94, 0xbfb8aa3b, v94
	v_mul_f32_e32 v90, 0xbfb8aa3b, v90
	v_mul_f32_e32 v95, 0xbfb8aa3b, v95
	v_mul_f32_e32 v91, 0xbfb8aa3b, v91
	v_exp_f32_e32 v92, v92
	v_exp_f32_e32 v88, v88
	v_exp_f32_e32 v93, v93
	v_exp_f32_e32 v89, v89
	v_exp_f32_e32 v94, v94
	v_exp_f32_e32 v90, v90
	v_exp_f32_e32 v95, v95
	v_exp_f32_e32 v91, v91
	v_add_f32_e32 v92, 1.0, v92
	v_add_f32_e32 v88, 1.0, v88
	v_add_f32_e32 v93, 1.0, v93
	v_add_f32_e32 v89, 1.0, v89
	v_add_f32_e32 v94, 1.0, v94
	v_add_f32_e32 v90, 1.0, v90
	v_add_f32_e32 v95, 1.0, v95
	v_add_f32_e32 v91, 1.0, v91
	v_rcp_f32_e32 v92, v92
	v_rcp_f32_e32 v88, v88
	v_rcp_f32_e32 v93, v93
	v_rcp_f32_e32 v89, v89
	v_rcp_f32_e32 v94, v94
	v_rcp_f32_e32 v90, v90
	v_rcp_f32_e32 v95, v95
	v_rcp_f32_e32 v91, v91
; __device__ __forceinline__ unsigned cvt_pk_bf16(float lo, float hi) { unsigned r; asm volatile("v_cvt_pk_bf16_f32 %0, %1, %2" : "=v"(r) : "v"(lo), "v"(hi)); return r; }
; __device__ __forceinline__ float sigmoid_f(float x) { return __builtin_amdgcn_rcpf(1.0f + __builtin_amdgcn_exp2f(-1.4426950408889634f * x)); }
;     __device__ __forceinline__ void operator()(const f32x4 (&acc)[2][2][4][2], const Unit& u, int wr, int wc, int fr, int fq) const {
;     ...
;             for (int ai = 0; ai < 2; ++ai)
; #pragma unroll
;                 for (int m = 0; m < 4; ++m) {
;                     f32x4 v0 = acc[ai][bj][m][0] + b0, v1 = acc[ai][bj][m][1] + b1;
;                     if (mode == 1) {
; #pragma unroll
;                         for (int e = 0; e < 4; ++e) { v0[e] = sigmoid_f(v0[e]); v1[e] = sigmoid_f(v1[e]); }
;                     }
;                     u32x4 w; w.x = cvt_pk_bf16(v0[0], v0[1]); w.y = cvt_pk_bf16(v0[2], v0[3]); w.z = cvt_pk_bf16(v1[0], v1[1]); w.w = cvt_pk_bf16(v1[2], v1[3]);
;                     *(u32x4*)(dst + (size_t)(row0 + ai * HALF + m * 16) * ldc + ct + c) = w;
;                 }
.LBB0_116:
	v_add_u32_e32 v96, 0x80, v165
	v_cvt_pk_bf16_f32 v92, v92, v93
	v_cvt_pk_bf16_f32 v93, v94, v95
	v_cvt_pk_bf16_f32 v94, v88, v89
	v_ashrrev_i32_e32 v88, 31, v96
	v_cvt_pk_bf16_f32 v95, v90, v91
	v_mul_u32_u24_e32 v88, s82, v96
	v_mov_b32_e32 v89, 0
	v_lshl_add_u64 v[88:89], v[88:89], 1, v[120:121]
	v_pk_add_f32 v[86:87], v[86:87], v[134:135]
	v_pk_add_f32 v[84:85], v[84:85], v[132:133]
	v_pk_add_f32 v[82:83], v[82:83], v[130:131]
	s_and_b64 vcc, exec, s[4:5]
	v_pk_add_f32 v[80:81], v[80:81], v[128:129]
	global_store_dwordx4 v[88:89], v[92:95], off
	s_cbranch_vccnz .LBB0_118
	v_mul_f32_e32 v84, 0xbfb8aa3b, v84
	v_mul_f32_e32 v80, 0xbfb8aa3b, v80
	v_mul_f32_e32 v85, 0xbfb8aa3b, v85
	v_mul_f32_e32 v81, 0xbfb8aa3b, v81
	v_mul_f32_e32 v86, 0xbfb8aa3b, v86
	v_mul_f32_e32 v82, 0xbfb8aa3b, v82
	v_mul_f32_e32 v87, 0xbfb8aa3b, v87
	v_mul_f32_e32 v83, 0xbfb8aa3b, v83
	v_exp_f32_e32 v84, v84
	v_exp_f32_e32 v80, v80
	v_exp_f32_e32 v85, v85
	v_exp_f32_e32 v81, v81
	v_exp_f32_e32 v86, v86
	v_exp_f32_e32 v82, v82
	v_exp_f32_e32 v87, v87
	v_exp_f32_e32 v83, v83
	v_add_f32_e32 v84, 1.0, v84
	v_add_f32_e32 v80, 1.0, v80
	v_add_f32_e32 v85, 1.0, v85
	v_add_f32_e32 v81, 1.0, v81
	v_add_f32_e32 v86, 1.0, v86
	v_add_f32_e32 v82, 1.0, v82
	v_add_f32_e32 v87, 1.0, v87
	v_add_f32_e32 v83, 1.0, v83
	v_rcp_f32_e32 v84, v84
	v_rcp_f32_e32 v80, v80
	v_rcp_f32_e32 v85, v85
	v_rcp_f32_e32 v81, v81
	v_rcp_f32_e32 v86, v86
	v_rcp_f32_e32 v82, v82
	v_rcp_f32_e32 v87, v87
	v_rcp_f32_e32 v83, v83
.LBB0_118:
	v_cvt_pk_bf16_f32 v84, v84, v85
	v_cvt_pk_bf16_f32 v85, v86, v87
	v_cvt_pk_bf16_f32 v86, v80, v81
	v_add_u32_e32 v80, 0x90, v165
	v_ashrrev_i32_e32 v81, 31, v80
	v_cvt_pk_bf16_f32 v87, v82, v83
	v_mul_u32_u24_e32 v80, s82, v80
	v_mov_b32_e32 v81, 0
	v_lshl_add_u64 v[80:81], v[80:81], 1, v[120:121]
	v_pk_add_f32 v[78:79], v[78:79], v[134:135]
	v_pk_add_f32 v[76:77], v[76:77], v[132:133]
	v_pk_add_f32 v[74:75], v[74:75], v[130:131]
	s_and_b64 vcc, exec, s[4:5]
	v_pk_add_f32 v[72:73], v[72:73], v[128:129]
	global_store_dwordx4 v[80:81], v[84:87], off
	s_cbranch_vccnz .LBB0_120
	v_mul_f32_e32 v76, 0xbfb8aa3b, v76
	v_mul_f32_e32 v72, 0xbfb8aa3b, v72
	v_mul_f32_e32 v77, 0xbfb8aa3b, v77
	v_mul_f32_e32 v73, 0xbfb8aa3b, v73
	v_mul_f32_e32 v78, 0xbfb8aa3b, v78
	v_mul_f32_e32 v74, 0xbfb8aa3b, v74
	v_mul_f32_e32 v79, 0xbfb8aa3b, v79
	v_mul_f32_e32 v75, 0xbfb8aa3b, v75
	v_exp_f32_e32 v76, v76
	v_exp_f32_e32 v72, v72
	v_exp_f32_e32 v77, v77
	v_exp_f32_e32 v73, v73
	v_exp_f32_e32 v78, v78
	v_exp_f32_e32 v74, v74
	v_exp_f32_e32 v79, v79
	v_exp_f32_e32 v75, v75
	v_add_f32_e32 v76, 1.0, v76
	v_add_f32_e32 v72, 1.0, v72
	v_add_f32_e32 v77, 1.0, v77
	v_add_f32_e32 v73, 1.0, v73
	v_add_f32_e32 v78, 1.0, v78
	v_add_f32_e32 v74, 1.0, v74
	v_add_f32_e32 v79, 1.0, v79
	v_add_f32_e32 v75, 1.0, v75
	v_rcp_f32_e32 v76, v76
	v_rcp_f32_e32 v72, v72
	v_rcp_f32_e32 v77, v77
	v_rcp_f32_e32 v73, v73
	v_rcp_f32_e32 v78, v78
	v_rcp_f32_e32 v74, v74
	v_rcp_f32_e32 v79, v79
	v_rcp_f32_e32 v75, v75
.LBB0_120:
	v_cvt_pk_bf16_f32 v76, v76, v77
	v_cvt_pk_bf16_f32 v77, v78, v79
	v_cvt_pk_bf16_f32 v78, v72, v73
	v_add_u32_e32 v72, 0xa0, v165
	v_ashrrev_i32_e32 v73, 31, v72
	v_cvt_pk_bf16_f32 v79, v74, v75
	v_mul_u32_u24_e32 v72, s82, v72
	v_mov_b32_e32 v73, 0
	v_lshl_add_u64 v[72:73], v[72:73], 1, v[120:121]
	v_pk_add_f32 v[70:71], v[70:71], v[134:135]
	v_pk_add_f32 v[68:69], v[68:69], v[132:133]
	v_pk_add_f32 v[66:67], v[66:67], v[130:131]
	s_and_b64 vcc, exec, s[4:5]
	v_pk_add_f32 v[64:65], v[64:65], v[128:129]
	global_store_dwordx4 v[72:73], v[76:79], off
	s_cbranch_vccnz .LBB0_122
	v_mul_f32_e32 v68, 0xbfb8aa3b, v68
	v_mul_f32_e32 v64, 0xbfb8aa3b, v64
	v_mul_f32_e32 v69, 0xbfb8aa3b, v69
	v_mul_f32_e32 v65, 0xbfb8aa3b, v65
	v_mul_f32_e32 v70, 0xbfb8aa3b, v70
	v_mul_f32_e32 v66, 0xbfb8aa3b, v66
	v_mul_f32_e32 v71, 0xbfb8aa3b, v71
	v_mul_f32_e32 v67, 0xbfb8aa3b, v67
	v_exp_f32_e32 v68, v68
	v_exp_f32_e32 v64, v64
	v_exp_f32_e32 v69, v69
	v_exp_f32_e32 v65, v65
	v_exp_f32_e32 v70, v70
	v_exp_f32_e32 v66, v66
	v_exp_f32_e32 v71, v71
	v_exp_f32_e32 v67, v67
	v_add_f32_e32 v68, 1.0, v68
	v_add_f32_e32 v64, 1.0, v64
	v_add_f32_e32 v69, 1.0, v69
	v_add_f32_e32 v65, 1.0, v65
	v_add_f32_e32 v70, 1.0, v70
	v_add_f32_e32 v66, 1.0, v66
	v_add_f32_e32 v71, 1.0, v71
	v_add_f32_e32 v67, 1.0, v67
	v_rcp_f32_e32 v68, v68
	v_rcp_f32_e32 v64, v64
	v_rcp_f32_e32 v69, v69
	v_rcp_f32_e32 v65, v65
	v_rcp_f32_e32 v70, v70
	v_rcp_f32_e32 v66, v66
	v_rcp_f32_e32 v71, v71
	v_rcp_f32_e32 v67, v67
.LBB0_122:
	v_cvt_pk_bf16_f32 v68, v68, v69
	v_cvt_pk_bf16_f32 v69, v70, v71
	v_cvt_pk_bf16_f32 v70, v64, v65
	v_add_u32_e32 v64, 0xb0, v165
	v_ashrrev_i32_e32 v65, 31, v64
	v_cvt_pk_bf16_f32 v71, v66, v67
	v_mul_u32_u24_e32 v64, s82, v64
	v_mov_b32_e32 v65, 0
	v_lshl_add_u64 v[64:65], v[64:65], 1, v[120:121]
	global_store_dwordx4 v[64:65], v[68:71], off
	s_xor_b64 s[88:89], s[88:89], -1
	s_andn2_b64 vcc, exec, s[88:89]
	s_cbranch_vccz .LBB0_125

; __device__ __forceinline__ unsigned cvt_pk_bf16(float lo, float hi) { unsigned r; asm volatile("v_cvt_pk_bf16_f32 %0, %1, %2" : "=v"(r) : "v"(lo), "v"(hi)); return r; }
; __device__ __forceinline__ float sigmoid_f(float x) { return __builtin_amdgcn_rcpf(1.0f + __builtin_amdgcn_exp2f(-1.4426950408889634f * x)); }
;     __device__ __forceinline__ void operator()(const f32x4 (&acc)[2][2][4][2], const Unit& u, int wr, int wc, int fr, int fq) const {
;     ...
;             for (int ai = 0; ai < 2; ++ai)
; #pragma unroll
;                 for (int m = 0; m < 4; ++m) {
;                     f32x4 v0 = acc[ai][bj][m][0] + b0, v1 = acc[ai][bj][m][1] + b1;
;                     if (mode == 1) {
; #pragma unroll
;                         for (int e = 0; e < 4; ++e) { v0[e] = sigmoid_f(v0[e]); v1[e] = sigmoid_f(v1[e]); }
;                     }
;                     u32x4 w; w.x = cvt_pk_bf16(v0[0], v0[1]); w.y = cvt_pk_bf16(v0[2], v0[3]); w.z = cvt_pk_bf16(v1[0], v1[1]); w.w = cvt_pk_bf16(v1[2], v1[3]);
;                     *(u32x4*)(dst + (size_t)(row0 + ai * HALF + m * 16) * ldc + ct + c) = w;
;                 }
.LBB0_129:
	v_cvt_pk_bf16_f32 v60, v60, v61
	v_cvt_pk_bf16_f32 v61, v62, v63
	v_cvt_pk_bf16_f32 v62, v72, v73
	v_cvt_pk_bf16_f32 v63, v58, v59
	v_ashrrev_i32_e32 v58, 31, v165
	v_lshlrev_b32_e32 v144, 1, v146
	v_mul_u32_u24_e32 v72, s82, v165
	v_mov_b32_e32 v73, 0
	v_lshl_add_u64 v[56:57], s[86:87], 0, v[144:145]
	v_lshl_add_u64 v[72:73], v[72:73], 1, v[56:57]
	v_pk_add_f32 v[54:55], v[54:55], v[70:71]
	v_pk_add_f32 v[52:53], v[52:53], v[68:69]
	v_pk_add_f32 v[50:51], v[50:51], v[66:67]
	s_and_b64 vcc, exec, s[4:5]
	v_pk_add_f32 v[48:49], v[48:49], v[64:65]
	global_store_dwordx4 v[72:73], v[60:63], off offset:256
	s_cbranch_vccnz .LBB0_131
	v_mul_f32_e32 v52, 0xbfb8aa3b, v52
	v_mul_f32_e32 v48, 0xbfb8aa3b, v48
	v_mul_f32_e32 v53, 0xbfb8aa3b, v53
	v_mul_f32_e32 v49, 0xbfb8aa3b, v49
	v_mul_f32_e32 v54, 0xbfb8aa3b, v54
	v_mul_f32_e32 v50, 0xbfb8aa3b, v50
	v_mul_f32_e32 v55, 0xbfb8aa3b, v55
	v_mul_f32_e32 v51, 0xbfb8aa3b, v51
	v_exp_f32_e32 v52, v52
	v_exp_f32_e32 v48, v48
	v_exp_f32_e32 v53, v53
	v_exp_f32_e32 v49, v49
	v_exp_f32_e32 v54, v54
	v_exp_f32_e32 v50, v50
	v_exp_f32_e32 v55, v55
	v_exp_f32_e32 v51, v51
	v_add_f32_e32 v52, 1.0, v52
	v_add_f32_e32 v48, 1.0, v48
	v_add_f32_e32 v53, 1.0, v53
	v_add_f32_e32 v49, 1.0, v49
	v_add_f32_e32 v54, 1.0, v54
	v_add_f32_e32 v50, 1.0, v50
	v_add_f32_e32 v55, 1.0, v55
	v_add_f32_e32 v51, 1.0, v51
	v_rcp_f32_e32 v52, v52
	v_rcp_f32_e32 v48, v48
	v_rcp_f32_e32 v53, v53
	v_rcp_f32_e32 v49, v49
	v_rcp_f32_e32 v54, v54
	v_rcp_f32_e32 v50, v50
	v_rcp_f32_e32 v55, v55
	v_rcp_f32_e32 v51, v51
.LBB0_131:
	v_cvt_pk_bf16_f32 v52, v52, v53
	v_cvt_pk_bf16_f32 v53, v54, v55
	v_cvt_pk_bf16_f32 v54, v48, v49
	v_or_b32_e32 v48, 16, v165
	v_cvt_pk_bf16_f32 v55, v50, v51
	v_mul_u32_u24_e32 v48, s82, v48
	v_mov_b32_e32 v49, 0
	v_lshl_add_u64 v[48:49], v[48:49], 1, v[56:57]
	v_pk_add_f32 v[46:47], v[46:47], v[70:71]
	v_pk_add_f32 v[44:45], v[44:45], v[68:69]
	v_pk_add_f32 v[42:43], v[42:43], v[66:67]
	s_and_b64 vcc, exec, s[4:5]
	v_pk_add_f32 v[40:41], v[40:41], v[64:65]
	global_store_dwordx4 v[48:49], v[52:55], off offset:256
	s_cbranch_vccnz .LBB0_133
	v_mul_f32_e32 v44, 0xbfb8aa3b, v44
	v_mul_f32_e32 v40, 0xbfb8aa3b, v40
	v_mul_f32_e32 v45, 0xbfb8aa3b, v45
	v_mul_f32_e32 v41, 0xbfb8aa3b, v41
	v_mul_f32_e32 v46, 0xbfb8aa3b, v46
	v_mul_f32_e32 v42, 0xbfb8aa3b, v42
	v_mul_f32_e32 v47, 0xbfb8aa3b, v47
	v_mul_f32_e32 v43, 0xbfb8aa3b, v43
	v_exp_f32_e32 v44, v44
	v_exp_f32_e32 v40, v40
	v_exp_f32_e32 v45, v45
	v_exp_f32_e32 v41, v41
	v_exp_f32_e32 v46, v46
	v_exp_f32_e32 v42, v42
	v_exp_f32_e32 v47, v47
	v_exp_f32_e32 v43, v43
	v_add_f32_e32 v44, 1.0, v44
	v_add_f32_e32 v40, 1.0, v40
	v_add_f32_e32 v45, 1.0, v45
	v_add_f32_e32 v41, 1.0, v41
	v_add_f32_e32 v46, 1.0, v46
	v_add_f32_e32 v42, 1.0, v42
	v_add_f32_e32 v47, 1.0, v47
	v_add_f32_e32 v43, 1.0, v43
	v_rcp_f32_e32 v44, v44
	v_rcp_f32_e32 v40, v40
	v_rcp_f32_e32 v45, v45
	v_rcp_f32_e32 v41, v41
	v_rcp_f32_e32 v46, v46
	v_rcp_f32_e32 v42, v42
	v_rcp_f32_e32 v47, v47
	v_rcp_f32_e32 v43, v43
.LBB0_133:
	v_cvt_pk_bf16_f32 v44, v44, v45
	v_cvt_pk_bf16_f32 v45, v46, v47
	v_cvt_pk_bf16_f32 v46, v40, v41
	v_or_b32_e32 v40, 32, v165
	v_cvt_pk_bf16_f32 v47, v42, v43
	v_mul_u32_u24_e32 v40, s82, v40
	v_mov_b32_e32 v41, 0
	v_lshl_add_u64 v[40:41], v[40:41], 1, v[56:57]
	v_pk_add_f32 v[38:39], v[38:39], v[70:71]
	v_pk_add_f32 v[36:37], v[36:37], v[68:69]
	v_pk_add_f32 v[34:35], v[34:35], v[66:67]
	s_and_b64 vcc, exec, s[4:5]
	v_pk_add_f32 v[32:33], v[32:33], v[64:65]
	global_store_dwordx4 v[40:41], v[44:47], off offset:256
	s_cbranch_vccnz .LBB0_135
	v_mul_f32_e32 v36, 0xbfb8aa3b, v36
	v_mul_f32_e32 v32, 0xbfb8aa3b, v32
	v_mul_f32_e32 v37, 0xbfb8aa3b, v37
	v_mul_f32_e32 v33, 0xbfb8aa3b, v33
	v_mul_f32_e32 v38, 0xbfb8aa3b, v38
	v_mul_f32_e32 v34, 0xbfb8aa3b, v34
	v_mul_f32_e32 v39, 0xbfb8aa3b, v39
	v_mul_f32_e32 v35, 0xbfb8aa3b, v35
	v_exp_f32_e32 v36, v36
	v_exp_f32_e32 v32, v32
	v_exp_f32_e32 v37, v37
	v_exp_f32_e32 v33, v33
	v_exp_f32_e32 v38, v38
	v_exp_f32_e32 v34, v34
	v_exp_f32_e32 v39, v39
	v_exp_f32_e32 v35, v35
	v_add_f32_e32 v36, 1.0, v36
	v_add_f32_e32 v32, 1.0, v32
	v_add_f32_e32 v37, 1.0, v37
	v_add_f32_e32 v33, 1.0, v33
	v_add_f32_e32 v38, 1.0, v38
	v_add_f32_e32 v34, 1.0, v34
	v_add_f32_e32 v39, 1.0, v39
	v_add_f32_e32 v35, 1.0, v35
	v_rcp_f32_e32 v36, v36
	v_rcp_f32_e32 v32, v32
	v_rcp_f32_e32 v37, v37
	v_rcp_f32_e32 v33, v33
	v_rcp_f32_e32 v38, v38
	v_rcp_f32_e32 v34, v34
	v_rcp_f32_e32 v39, v39
	v_rcp_f32_e32 v35, v35
.LBB0_135:
	v_cvt_pk_bf16_f32 v36, v36, v37
	v_cvt_pk_bf16_f32 v37, v38, v39
	v_cvt_pk_bf16_f32 v38, v32, v33
	v_or_b32_e32 v32, 48, v165
	v_cvt_pk_bf16_f32 v39, v34, v35
	v_mul_u32_u24_e32 v32, s82, v32
	v_mov_b32_e32 v33, 0
	v_lshl_add_u64 v[32:33], v[32:33], 1, v[56:57]
	v_pk_add_f32 v[30:31], v[30:31], v[70:71]
	v_pk_add_f32 v[28:29], v[28:29], v[68:69]
	v_pk_add_f32 v[26:27], v[26:27], v[66:67]
	s_and_b64 vcc, exec, s[4:5]
	v_pk_add_f32 v[24:25], v[24:25], v[64:65]
	global_store_dwordx4 v[32:33], v[36:39], off offset:256
	s_cbranch_vccnz .LBB0_137
	v_mul_f32_e32 v28, 0xbfb8aa3b, v28
	v_mul_f32_e32 v24, 0xbfb8aa3b, v24
	v_mul_f32_e32 v29, 0xbfb8aa3b, v29
	v_mul_f32_e32 v25, 0xbfb8aa3b, v25
	v_mul_f32_e32 v30, 0xbfb8aa3b, v30
	v_mul_f32_e32 v26, 0xbfb8aa3b, v26
	v_mul_f32_e32 v31, 0xbfb8aa3b, v31
	v_mul_f32_e32 v27, 0xbfb8aa3b, v27
	v_exp_f32_e32 v28, v28
	v_exp_f32_e32 v24, v24
	v_exp_f32_e32 v29, v29
	v_exp_f32_e32 v25, v25
	v_exp_f32_e32 v30, v30
	v_exp_f32_e32 v26, v26
	v_exp_f32_e32 v31, v31
	v_exp_f32_e32 v27, v27
	v_add_f32_e32 v28, 1.0, v28
	v_add_f32_e32 v24, 1.0, v24
	v_add_f32_e32 v29, 1.0, v29
	v_add_f32_e32 v25, 1.0, v25
	v_add_f32_e32 v30, 1.0, v30
	v_add_f32_e32 v26, 1.0, v26
	v_add_f32_e32 v31, 1.0, v31
	v_add_f32_e32 v27, 1.0, v27
	v_rcp_f32_e32 v28, v28
	v_rcp_f32_e32 v24, v24
	v_rcp_f32_e32 v29, v29
	v_rcp_f32_e32 v25, v25
	v_rcp_f32_e32 v30, v30
	v_rcp_f32_e32 v26, v26
	v_rcp_f32_e32 v31, v31
	v_rcp_f32_e32 v27, v27
; __device__ __forceinline__ unsigned cvt_pk_bf16(float lo, float hi) { unsigned r; asm volatile("v_cvt_pk_bf16_f32 %0, %1, %2" : "=v"(r) : "v"(lo), "v"(hi)); return r; }
; __device__ __forceinline__ float sigmoid_f(float x) { return __builtin_amdgcn_rcpf(1.0f + __builtin_amdgcn_exp2f(-1.4426950408889634f * x)); }
;     __device__ __forceinline__ void operator()(const f32x4 (&acc)[2][2][4][2], const Unit& u, int wr, int wc, int fr, int fq) const {
;     ...
;             for (int ai = 0; ai < 2; ++ai)
; #pragma unroll
;                 for (int m = 0; m < 4; ++m) {
;                     f32x4 v0 = acc[ai][bj][m][0] + b0, v1 = acc[ai][bj][m][1] + b1;
;                     if (mode == 1) {
; #pragma unroll
;                         for (int e = 0; e < 4; ++e) { v0[e] = sigmoid_f(v0[e]); v1[e] = sigmoid_f(v1[e]); }
;                     }
;                     u32x4 w; w.x = cvt_pk_bf16(v0[0], v0[1]); w.y = cvt_pk_bf16(v0[2], v0[3]); w.z = cvt_pk_bf16(v1[0], v1[1]); w.w = cvt_pk_bf16(v1[2], v1[3]);
;                     *(u32x4*)(dst + (size_t)(row0 + ai * HALF + m * 16) * ldc + ct + c) = w;
;                 }
.LBB0_137:
	v_add_u32_e32 v32, 0x80, v165
	v_cvt_pk_bf16_f32 v28, v28, v29
	v_cvt_pk_bf16_f32 v29, v30, v31
	v_cvt_pk_bf16_f32 v30, v24, v25
	v_ashrrev_i32_e32 v24, 31, v32
	v_cvt_pk_bf16_f32 v31, v26, v27
	v_mul_u32_u24_e32 v24, s82, v32
	v_mov_b32_e32 v25, 0
	v_lshl_add_u64 v[24:25], v[24:25], 1, v[56:57]
	v_pk_add_f32 v[22:23], v[22:23], v[70:71]
	v_pk_add_f32 v[20:21], v[20:21], v[68:69]
	v_pk_add_f32 v[18:19], v[18:19], v[66:67]
	s_and_b64 vcc, exec, s[4:5]
	v_pk_add_f32 v[16:17], v[16:17], v[64:65]
	global_store_dwordx4 v[24:25], v[28:31], off offset:256
	s_cbranch_vccnz .LBB0_139
	v_mul_f32_e32 v20, 0xbfb8aa3b, v20
	v_mul_f32_e32 v16, 0xbfb8aa3b, v16
	v_mul_f32_e32 v21, 0xbfb8aa3b, v21
	v_mul_f32_e32 v17, 0xbfb8aa3b, v17
	v_mul_f32_e32 v22, 0xbfb8aa3b, v22
	v_mul_f32_e32 v18, 0xbfb8aa3b, v18
	v_mul_f32_e32 v23, 0xbfb8aa3b, v23
	v_mul_f32_e32 v19, 0xbfb8aa3b, v19
	v_exp_f32_e32 v20, v20
	v_exp_f32_e32 v16, v16
	v_exp_f32_e32 v21, v21
	v_exp_f32_e32 v17, v17
	v_exp_f32_e32 v22, v22
	v_exp_f32_e32 v18, v18
	v_exp_f32_e32 v23, v23
	v_exp_f32_e32 v19, v19
	v_add_f32_e32 v20, 1.0, v20
	v_add_f32_e32 v16, 1.0, v16
	v_add_f32_e32 v21, 1.0, v21
	v_add_f32_e32 v17, 1.0, v17
	v_add_f32_e32 v22, 1.0, v22
	v_add_f32_e32 v18, 1.0, v18
	v_add_f32_e32 v23, 1.0, v23
	v_add_f32_e32 v19, 1.0, v19
	v_rcp_f32_e32 v20, v20
	v_rcp_f32_e32 v16, v16
	v_rcp_f32_e32 v21, v21
	v_rcp_f32_e32 v17, v17
	v_rcp_f32_e32 v22, v22
	v_rcp_f32_e32 v18, v18
	v_rcp_f32_e32 v23, v23
	v_rcp_f32_e32 v19, v19
.LBB0_139:
	v_cvt_pk_bf16_f32 v20, v20, v21
	v_cvt_pk_bf16_f32 v21, v22, v23
	v_cvt_pk_bf16_f32 v22, v16, v17
	v_add_u32_e32 v16, 0x90, v165
	v_ashrrev_i32_e32 v17, 31, v16
	v_cvt_pk_bf16_f32 v23, v18, v19
	v_mul_u32_u24_e32 v16, s82, v16
	v_mov_b32_e32 v17, 0
	v_lshl_add_u64 v[16:17], v[16:17], 1, v[56:57]
	v_pk_add_f32 v[14:15], v[14:15], v[70:71]
	v_pk_add_f32 v[12:13], v[12:13], v[68:69]
	v_pk_add_f32 v[10:11], v[10:11], v[66:67]
	s_and_b64 vcc, exec, s[4:5]
	v_pk_add_f32 v[8:9], v[8:9], v[64:65]
	global_store_dwordx4 v[16:17], v[20:23], off offset:256
	s_cbranch_vccnz .LBB0_141
	v_mul_f32_e32 v12, 0xbfb8aa3b, v12
	v_mul_f32_e32 v8, 0xbfb8aa3b, v8
	v_mul_f32_e32 v13, 0xbfb8aa3b, v13
	v_mul_f32_e32 v9, 0xbfb8aa3b, v9
	v_mul_f32_e32 v14, 0xbfb8aa3b, v14
	v_mul_f32_e32 v10, 0xbfb8aa3b, v10
	v_mul_f32_e32 v15, 0xbfb8aa3b, v15
	v_mul_f32_e32 v11, 0xbfb8aa3b, v11
	v_exp_f32_e32 v12, v12
	v_exp_f32_e32 v8, v8
	v_exp_f32_e32 v13, v13
	v_exp_f32_e32 v9, v9
	v_exp_f32_e32 v14, v14
	v_exp_f32_e32 v10, v10
	v_exp_f32_e32 v15, v15
	v_exp_f32_e32 v11, v11
	v_add_f32_e32 v12, 1.0, v12
	v_add_f32_e32 v8, 1.0, v8
	v_add_f32_e32 v13, 1.0, v13
	v_add_f32_e32 v9, 1.0, v9
	v_add_f32_e32 v14, 1.0, v14
	v_add_f32_e32 v10, 1.0, v10
	v_add_f32_e32 v15, 1.0, v15
	v_add_f32_e32 v11, 1.0, v11
	v_rcp_f32_e32 v12, v12
	v_rcp_f32_e32 v8, v8
	v_rcp_f32_e32 v13, v13
	v_rcp_f32_e32 v9, v9
	v_rcp_f32_e32 v14, v14
	v_rcp_f32_e32 v10, v10
	v_rcp_f32_e32 v15, v15
	v_rcp_f32_e32 v11, v11
.LBB0_141:
	v_cvt_pk_bf16_f32 v12, v12, v13
	v_cvt_pk_bf16_f32 v13, v14, v15
	v_cvt_pk_bf16_f32 v14, v8, v9
	v_add_u32_e32 v8, 0xa0, v165
	v_ashrrev_i32_e32 v9, 31, v8
	v_cvt_pk_bf16_f32 v15, v10, v11
	v_mul_u32_u24_e32 v8, s82, v8
	v_mov_b32_e32 v9, 0
	v_lshl_add_u64 v[8:9], v[8:9], 1, v[56:57]
	v_pk_add_f32 v[6:7], v[6:7], v[70:71]
	v_pk_add_f32 v[4:5], v[4:5], v[68:69]
	v_pk_add_f32 v[2:3], v[2:3], v[66:67]
	s_and_b64 vcc, exec, s[4:5]
	v_pk_add_f32 v[0:1], v[0:1], v[64:65]
	global_store_dwordx4 v[8:9], v[12:15], off offset:256
	s_cbranch_vccnz .LBB0_143
	v_mul_f32_e32 v4, 0xbfb8aa3b, v4
	v_mul_f32_e32 v0, 0xbfb8aa3b, v0
	v_mul_f32_e32 v5, 0xbfb8aa3b, v5
	v_mul_f32_e32 v1, 0xbfb8aa3b, v1
	v_mul_f32_e32 v6, 0xbfb8aa3b, v6
	v_mul_f32_e32 v2, 0xbfb8aa3b, v2
	v_mul_f32_e32 v7, 0xbfb8aa3b, v7
	v_mul_f32_e32 v3, 0xbfb8aa3b, v3
	v_exp_f32_e32 v4, v4
	v_exp_f32_e32 v0, v0
	v_exp_f32_e32 v5, v5
	v_exp_f32_e32 v1, v1
	v_exp_f32_e32 v6, v6
	v_exp_f32_e32 v2, v2
	v_exp_f32_e32 v7, v7
	v_exp_f32_e32 v3, v3
	v_add_f32_e32 v4, 1.0, v4
	v_add_f32_e32 v0, 1.0, v0
	v_add_f32_e32 v5, 1.0, v5
	v_add_f32_e32 v1, 1.0, v1
	v_add_f32_e32 v6, 1.0, v6
	v_add_f32_e32 v2, 1.0, v2
	v_add_f32_e32 v7, 1.0, v7
	v_add_f32_e32 v3, 1.0, v3
	v_rcp_f32_e32 v4, v4
	v_rcp_f32_e32 v0, v0
	v_rcp_f32_e32 v5, v5
	v_rcp_f32_e32 v1, v1
	v_rcp_f32_e32 v6, v6
	v_rcp_f32_e32 v2, v2
	v_rcp_f32_e32 v7, v7
	v_rcp_f32_e32 v3, v3
.LBB0_143:
	v_cvt_pk_bf16_f32 v4, v4, v5
	v_cvt_pk_bf16_f32 v5, v6, v7
	v_cvt_pk_bf16_f32 v6, v0, v1
	v_add_u32_e32 v0, 0xb0, v165
	v_ashrrev_i32_e32 v1, 31, v0
	v_cvt_pk_bf16_f32 v7, v2, v3
	v_mul_u32_u24_e32 v0, s82, v0
	v_mov_b32_e32 v1, 0
	v_lshl_add_u64 v[0:1], v[0:1], 1, v[56:57]
	global_store_dwordx4 v[0:1], v[4:7], off offset:256
	s_andn2_b64 vcc, exec, s[0:1]
	s_mov_b64 s[0:1], -1
	s_cbranch_vccnz .LBB0_83
